# k-loop: whole DMA block issued right after the k-tile barrier, ahead of the first-group reads and the last group's MFMAs (earliest possible DMA issue)
# baseline (speedup 1.0000x reference)
; #define MFMA(a, b, c) __builtin_amdgcn_mfma_f32_32x32x16_bf16((a), (b), (c), 0, 0, 0)
;     ...
;     auto issue_at = [&](int mm0, int nn0, int kt, int buf) {
;       char* lb = L0 + buf * BUFB;
; #pragma unroll
;       for (int i = 0; i < 4; ++i) {
;         const int seg = wv * 4 + i, row = seg * 8 + gl_row;
;         const int c = (lane & 7) ^ ((row >> 1) & 7);
;         const u16* ap = (kt < g.split) ? g.a0 + (size_t)(mm0 + row) * g.ld0 + kt * g.ks0 : g.a1 + (size_t)(mm0 + row) * g.ld1 + (kt - g.split) * 64;
;         __builtin_amdgcn_global_load_lds((const unsigned*)(ap + c * 8), (__attribute__((address_space(3))) unsigned*)(lb + seg * 1024 + lane * 16), 16, 0, 0);
;       }
; #pragma unroll
;       for (int i = 0; i < BN / 64; ++i) {
;         const int seg = wv * (BN / 64) + i, row = seg * 8 + gl_row;
;         const int c = (lane & 7) ^ ((row >> 1) & 7);
;         __builtin_amdgcn_global_load_lds((const unsigned*)(g.W + (size_t)(nn0 + row) * g.K + kt * 64 + c * 8),
;                                          (__attribute__((address_space(3))) unsigned*)(lb + 256 * 128 + seg * 1024 + lane * 16), 16, 0, 0);
;       }
;     ...
;     auto compute2 = [&](int buf) {
;       const char* lb = L0 + buf * BUFB;
; #pragma unroll
;       for (int ks = 0; ks < 4; ++ks) {
;         const int c = ks * 2 + hh;
;         bf16x8 wf[2], xf[MI];
; #pragma unroll
;         for (int j = 0; j < 2; ++j) { const int r = wn * 64 + j * 32 + l32; wf[j] = *(const bf16x8*)(lb + 256 * 128 + r * 128 + ((c ^ ((r >> 1) & 7)) << 4)); }
; #pragma unroll
;         for (int i = 0; i < MI; ++i) { const int r = wm * (MI * 32) + i * 32 + l32; xf[i] = *(const bf16x8*)(lb + r * 128 + ((c ^ ((r >> 1) & 7)) << 4)); }
; #pragma unroll
;         for (int i = 0; i < MI; ++i) {
;           acc[i][0] = MFMA(wf[0], xf[i], acc[i][0]);
;           acc[i][1] = MFMA(wf[1], xf[i], acc[i][1]);
;         }
;       }
.Lgemm_prio_798:
	s_and_b32 s14, s11, 0x10000
	s_xor_b32 s15, s14, 0x10000
	s_add_i32 s15, s15, 0
	s_add_i32 s14, s14, 0
	v_add_u32_e32 v0, s14, v175
	v_add_u32_e32 v254, v0, v171
	v_add_u32_e32 v0, v0, v170
	ds_read_b128 v[200:203], v254 offset:32768
	ds_read_b128 v[204:207], v254 offset:36864
	ds_read_b128 v[208:211], v0
	ds_read_b128 v[212:215], v0 offset:4096
	ds_read_b128 v[216:219], v0 offset:8192
	ds_read_b128 v[220:223], v0 offset:12288
	s_add_i32 s64, s15, 0x8000
	s_add_i32 m0, s15, s60
	v_lshl_add_u64 v[176:177], v[152:153], 0, s[2:3]
	global_load_lds_dwordx4 v[176:177], off
	s_add_i32 m0, s15, s61
	v_lshl_add_u64 v[176:177], v[150:151], 0, s[2:3]
	global_load_lds_dwordx4 v[176:177], off
	s_add_i32 m0, s15, s62
	v_lshl_add_u64 v[176:177], v[148:149], 0, s[2:3]
	global_load_lds_dwordx4 v[176:177], off
	s_add_i32 m0, s15, s63
	v_lshl_add_u64 v[176:177], v[146:147], 0, s[2:3]
	global_load_lds_dwordx4 v[176:177], off
	s_add_i32 m0, s64, s60
	v_lshl_add_u64 v[176:177], v[144:145], 0, s[2:3]
	global_load_lds_dwordx4 v[176:177], off
	s_add_i32 m0, s64, s61
	v_lshl_add_u64 v[176:177], v[142:143], 0, s[2:3]
	global_load_lds_dwordx4 v[176:177], off
	s_add_i32 m0, s64, s62
	v_lshl_add_u64 v[176:177], v[140:141], 0, s[2:3]
	global_load_lds_dwordx4 v[176:177], off
	s_add_i32 m0, s64, s63
	v_lshl_add_u64 v[176:177], v[138:139], 0, s[2:3]
	global_load_lds_dwordx4 v[176:177], off
	v_add_u32_e32 v0, s14, v174
	v_add_u32_e32 v254, v0, v171
	v_add_u32_e32 v0, v0, v170
	s_waitcnt lgkmcnt(3)
	v_mfma_f32_32x32x16_bf16 v[114:129], v[200:203], v[208:211], 0
	s_add_i32 s11, s11, 0x10000
	s_add_u32 s2, s2, 0x80
	s_addc_u32 s3, s3, 0
	s_cmpk_eq_i32 s2, 0x780
	ds_read_b128 v[224:227], v254 offset:32768
	v_mfma_f32_32x32x16_bf16 v[98:113], v[204:207], v[208:211], 0
	ds_read_b128 v[228:231], v254 offset:36864
	s_waitcnt lgkmcnt(4)
	v_mfma_f32_32x32x16_bf16 v[82:97], v[200:203], v[212:215], 0
	ds_read_b128 v[232:235], v0
	v_mfma_f32_32x32x16_bf16 v[66:81], v[204:207], v[212:215], 0
	ds_read_b128 v[240:243], v0 offset:4096
	s_waitcnt lgkmcnt(5)
	v_mfma_f32_32x32x16_bf16 v[50:65], v[200:203], v[216:219], 0
	ds_read_b128 v[244:247], v0 offset:8192
	v_mfma_f32_32x32x16_bf16 v[34:49], v[204:207], v[216:219], 0
	ds_read_b128 v[248:251], v0 offset:12288
	s_waitcnt lgkmcnt(6)
	v_mfma_f32_32x32x16_bf16 v[18:33], v[200:203], v[220:223], 0
	v_mfma_f32_32x32x16_bf16 v[2:17], v[204:207], v[220:223], 0
	s_branch .Lgemm_g1_798
.Lgemm_rot_798:
	v_add_u32_e32 v0, s14, v174
	v_add_u32_e32 v254, v0, v171
	v_add_u32_e32 v0, v0, v170
	s_waitcnt lgkmcnt(3)
	v_mfma_f32_32x32x16_bf16 v[114:129], v[200:203], v[208:211], v[114:129]
	s_add_i32 s11, s11, 0x10000
	s_add_u32 s2, s2, 0x80
	s_addc_u32 s3, s3, 0
	s_cmpk_eq_i32 s2, 0x780
	ds_read_b128 v[224:227], v254 offset:32768
	v_mfma_f32_32x32x16_bf16 v[98:113], v[204:207], v[208:211], v[98:113]
	ds_read_b128 v[228:231], v254 offset:36864
	s_waitcnt lgkmcnt(4)
	v_mfma_f32_32x32x16_bf16 v[82:97], v[200:203], v[212:215], v[82:97]
	ds_read_b128 v[232:235], v0
	v_mfma_f32_32x32x16_bf16 v[66:81], v[204:207], v[212:215], v[66:81]
	ds_read_b128 v[240:243], v0 offset:4096
	s_waitcnt lgkmcnt(5)
	v_mfma_f32_32x32x16_bf16 v[50:65], v[200:203], v[216:219], v[50:65]
	ds_read_b128 v[244:247], v0 offset:8192
	v_mfma_f32_32x32x16_bf16 v[34:49], v[204:207], v[216:219], v[34:49]
	ds_read_b128 v[248:251], v0 offset:12288
	s_waitcnt lgkmcnt(6)
	v_mfma_f32_32x32x16_bf16 v[18:33], v[200:203], v[220:223], v[18:33]
	v_mfma_f32_32x32x16_bf16 v[2:17], v[204:207], v[220:223], v[2:17]
; #define MFMA(a, b, c) __builtin_amdgcn_mfma_f32_32x32x16_bf16((a), (b), (c), 0, 0, 0)
;     ...
;     auto issue_at = [&](int mm0, int nn0, int kt, int buf) {
;       char* lb = L0 + buf * BUFB;
; #pragma unroll
;       for (int i = 0; i < 4; ++i) {
;         const int seg = wv * 4 + i, row = seg * 8 + gl_row;
;         const int c = (lane & 7) ^ ((row >> 1) & 7);
;         const u16* ap = (kt < g.split) ? g.a0 + (size_t)(mm0 + row) * g.ld0 + kt * g.ks0 : g.a1 + (size_t)(mm0 + row) * g.ld1 + (kt - g.split) * 64;
;         __builtin_amdgcn_global_load_lds((const unsigned*)(ap + c * 8), (__attribute__((address_space(3))) unsigned*)(lb + seg * 1024 + lane * 16), 16, 0, 0);
;       }
; #pragma unroll
;       for (int i = 0; i < BN / 64; ++i) {
;         const int seg = wv * (BN / 64) + i, row = seg * 8 + gl_row;
;         const int c = (lane & 7) ^ ((row >> 1) & 7);
;         __builtin_amdgcn_global_load_lds((const unsigned*)(g.W + (size_t)(nn0 + row) * g.K + kt * 64 + c * 8),
;                                          (__attribute__((address_space(3))) unsigned*)(lb + 256 * 128 + seg * 1024 + lane * 16), 16, 0, 0);
;       }
;     ...
;     auto compute2 = [&](int buf) {
;       const char* lb = L0 + buf * BUFB;
; #pragma unroll
;       for (int ks = 0; ks < 4; ++ks) {
;         const int c = ks * 2 + hh;
;         bf16x8 wf[2], xf[MI];
; #pragma unroll
;         for (int j = 0; j < 2; ++j) { const int r = wn * 64 + j * 32 + l32; wf[j] = *(const bf16x8*)(lb + 256 * 128 + r * 128 + ((c ^ ((r >> 1) & 7)) << 4)); }
; #pragma unroll
;         for (int i = 0; i < MI; ++i) { const int r = wm * (MI * 32) + i * 32 + l32; xf[i] = *(const bf16x8*)(lb + r * 128 + ((c ^ ((r >> 1) & 7)) << 4)); }
; #pragma unroll
;         for (int i = 0; i < MI; ++i) {
;           acc[i][0] = MFMA(wf[0], xf[i], acc[i][0]);
;           acc[i][1] = MFMA(wf[1], xf[i], acc[i][1]);
;         }
;       }
.Lgemm_g1_798:
	v_add_u32_e32 v0, s14, v173
	v_add_u32_e32 v254, v0, v171
	v_add_u32_e32 v0, v0, v170
	s_waitcnt lgkmcnt(3)
	v_mfma_f32_32x32x16_bf16 v[114:129], v[224:227], v[232:235], v[114:129]
	ds_read_b128 v[200:203], v254 offset:32768
	v_mfma_f32_32x32x16_bf16 v[98:113], v[228:231], v[232:235], v[98:113]
	ds_read_b128 v[204:207], v254 offset:36864
	s_waitcnt lgkmcnt(4)
	v_mfma_f32_32x32x16_bf16 v[82:97], v[224:227], v[240:243], v[82:97]
	ds_read_b128 v[208:211], v0
	v_mfma_f32_32x32x16_bf16 v[66:81], v[228:231], v[240:243], v[66:81]
	ds_read_b128 v[212:215], v0 offset:4096
	s_waitcnt lgkmcnt(5)
	v_mfma_f32_32x32x16_bf16 v[50:65], v[224:227], v[244:247], v[50:65]
	ds_read_b128 v[216:219], v0 offset:8192
	v_mfma_f32_32x32x16_bf16 v[34:49], v[228:231], v[244:247], v[34:49]
	ds_read_b128 v[220:223], v0 offset:12288
	s_waitcnt lgkmcnt(6)
	v_mfma_f32_32x32x16_bf16 v[18:33], v[224:227], v[248:251], v[18:33]
	v_mfma_f32_32x32x16_bf16 v[2:17], v[228:231], v[248:251], v[2:17]
	v_add_u32_e32 v0, s14, v172
	v_add_u32_e32 v254, v0, v171
	v_add_u32_e32 v0, v0, v170
	s_waitcnt lgkmcnt(3)
	v_mfma_f32_32x32x16_bf16 v[114:129], v[200:203], v[208:211], v[114:129]
	ds_read_b128 v[224:227], v254 offset:32768
	v_mfma_f32_32x32x16_bf16 v[98:113], v[204:207], v[208:211], v[98:113]
	ds_read_b128 v[228:231], v254 offset:36864
	s_waitcnt lgkmcnt(4)
	v_mfma_f32_32x32x16_bf16 v[82:97], v[200:203], v[212:215], v[82:97]
	ds_read_b128 v[232:235], v0
	v_mfma_f32_32x32x16_bf16 v[66:81], v[204:207], v[212:215], v[66:81]
	ds_read_b128 v[240:243], v0 offset:4096
	s_waitcnt lgkmcnt(5)
	v_mfma_f32_32x32x16_bf16 v[50:65], v[200:203], v[216:219], v[50:65]
	ds_read_b128 v[244:247], v0 offset:8192
	v_mfma_f32_32x32x16_bf16 v[34:49], v[204:207], v[216:219], v[34:49]
	ds_read_b128 v[248:251], v0 offset:12288
	s_waitcnt lgkmcnt(6)
	v_mfma_f32_32x32x16_bf16 v[18:33], v[200:203], v[220:223], v[18:33]
	v_mfma_f32_32x32x16_bf16 v[2:17], v[204:207], v[220:223], v[2:17]
	s_waitcnt vmcnt(0)
	s_waitcnt vmcnt(0) lgkmcnt(0)
	s_barrier
	s_cbranch_scc1 .Lgemm_exit_798
	s_and_b32 s14, s11, 0x10000
	s_xor_b32 s15, s14, 0x10000
	s_add_i32 s15, s15, 0
	s_add_i32 s14, s14, 0
	v_add_u32_e32 v0, s14, v175
	v_add_u32_e32 v254, v0, v171
	v_add_u32_e32 v0, v0, v170
	s_add_i32 s64, s15, 0x8000
	s_add_i32 m0, s15, s60
	v_lshl_add_u64 v[176:177], v[152:153], 0, s[2:3]
	global_load_lds_dwordx4 v[176:177], off
	s_add_i32 m0, s15, s61
	v_lshl_add_u64 v[176:177], v[150:151], 0, s[2:3]
	global_load_lds_dwordx4 v[176:177], off
	s_add_i32 m0, s15, s62
	v_lshl_add_u64 v[176:177], v[148:149], 0, s[2:3]
	global_load_lds_dwordx4 v[176:177], off
	s_add_i32 m0, s15, s63
	v_lshl_add_u64 v[176:177], v[146:147], 0, s[2:3]
	global_load_lds_dwordx4 v[176:177], off
	s_add_i32 m0, s64, s60
	v_lshl_add_u64 v[176:177], v[144:145], 0, s[2:3]
	global_load_lds_dwordx4 v[176:177], off
	s_add_i32 m0, s64, s61
	v_lshl_add_u64 v[176:177], v[142:143], 0, s[2:3]
	global_load_lds_dwordx4 v[176:177], off
	s_add_i32 m0, s64, s62
	v_lshl_add_u64 v[176:177], v[140:141], 0, s[2:3]
	global_load_lds_dwordx4 v[176:177], off
	s_add_i32 m0, s64, s63
	v_lshl_add_u64 v[176:177], v[138:139], 0, s[2:3]
	global_load_lds_dwordx4 v[176:177], off
	ds_read_b128 v[200:203], v254 offset:32768
	ds_read_b128 v[204:207], v254 offset:36864
	ds_read_b128 v[208:211], v0
	ds_read_b128 v[212:215], v0 offset:4096
	ds_read_b128 v[216:219], v0 offset:8192
	ds_read_b128 v[220:223], v0 offset:12288
	v_mfma_f32_32x32x16_bf16 v[114:129], v[224:227], v[232:235], v[114:129]
	v_mfma_f32_32x32x16_bf16 v[98:113], v[228:231], v[232:235], v[98:113]
	v_mfma_f32_32x32x16_bf16 v[82:97], v[224:227], v[240:243], v[82:97]
	v_mfma_f32_32x32x16_bf16 v[66:81], v[228:231], v[240:243], v[66:81]
	v_mfma_f32_32x32x16_bf16 v[50:65], v[224:227], v[244:247], v[50:65]
	v_mfma_f32_32x32x16_bf16 v[34:49], v[228:231], v[244:247], v[34:49]
	v_mfma_f32_32x32x16_bf16 v[18:33], v[224:227], v[248:251], v[18:33]
	v_mfma_f32_32x32x16_bf16 v[2:17], v[228:231], v[248:251], v[2:17]
	s_branch .Lgemm_rot_798

; #define MFMA(a, b, c) __builtin_amdgcn_mfma_f32_32x32x16_bf16((a), (b), (c), 0, 0, 0)
;     ...
;     auto issue_at = [&](int mm0, int nn0, int kt, int buf) {
;       char* lb = L0 + buf * BUFB;
; #pragma unroll
;       for (int i = 0; i < 4; ++i) {
;         const int seg = wv * 4 + i, row = seg * 8 + gl_row;
;         const int c = (lane & 7) ^ ((row >> 1) & 7);
;         const u16* ap = (kt < g.split) ? g.a0 + (size_t)(mm0 + row) * g.ld0 + kt * g.ks0 : g.a1 + (size_t)(mm0 + row) * g.ld1 + (kt - g.split) * 64;
;         __builtin_amdgcn_global_load_lds((const unsigned*)(ap + c * 8), (__attribute__((address_space(3))) unsigned*)(lb + seg * 1024 + lane * 16), 16, 0, 0);
;       }
; #pragma unroll
;       for (int i = 0; i < BN / 64; ++i) {
;         const int seg = wv * (BN / 64) + i, row = seg * 8 + gl_row;
;         const int c = (lane & 7) ^ ((row >> 1) & 7);
;         __builtin_amdgcn_global_load_lds((const unsigned*)(g.W + (size_t)(nn0 + row) * g.K + kt * 64 + c * 8),
;                                          (__attribute__((address_space(3))) unsigned*)(lb + 256 * 128 + seg * 1024 + lane * 16), 16, 0, 0);
;       }
;     ...
;     auto compute2 = [&](int buf) {
;       const char* lb = L0 + buf * BUFB;
; #pragma unroll
;       for (int ks = 0; ks < 4; ++ks) {
;         const int c = ks * 2 + hh;
;         bf16x8 wf[2], xf[MI];
; #pragma unroll
;         for (int j = 0; j < 2; ++j) { const int r = wn * 64 + j * 32 + l32; wf[j] = *(const bf16x8*)(lb + 256 * 128 + r * 128 + ((c ^ ((r >> 1) & 7)) << 4)); }
; #pragma unroll
;         for (int i = 0; i < MI; ++i) { const int r = wm * (MI * 32) + i * 32 + l32; xf[i] = *(const bf16x8*)(lb + r * 128 + ((c ^ ((r >> 1) & 7)) << 4)); }
; #pragma unroll
;         for (int i = 0; i < MI; ++i) {
;           acc[i][0] = MFMA(wf[0], xf[i], acc[i][0]);
;           acc[i][1] = MFMA(wf[1], xf[i], acc[i][1]);
;         }
;       }
.Lgemm_g1_1274:
	v_add_u32_e32 v233, s59, v199
	v_add_u32_e32 v230, v233, v175
	v_add_u32_e32 v234, v233, v174
	s_waitcnt lgkmcnt(3)
	v_mfma_f32_32x32x16_bf16 v[114:129], v[240:243], v[248:251], v[114:129]
	ds_read_b128 v[202:205], v230 offset:32768
	v_mfma_f32_32x32x16_bf16 v[98:113], v[244:247], v[248:251], v[98:113]
	ds_read_b128 v[206:209], v230 offset:36864
	s_waitcnt lgkmcnt(4)
	v_mfma_f32_32x32x16_bf16 v[82:97], v[240:243], v[214:217], v[82:97]
	ds_read_b128 v[210:213], v234
	v_mfma_f32_32x32x16_bf16 v[66:81], v[244:247], v[214:217], v[66:81]
	ds_read_b128 v[214:217], v234 offset:4096
	s_waitcnt lgkmcnt(5)
	v_mfma_f32_32x32x16_bf16 v[50:65], v[240:243], v[218:221], v[50:65]
	v_mfma_f32_32x32x16_bf16 v[34:49], v[244:247], v[218:221], v[34:49]
	ds_read_b128 v[218:221], v234 offset:8192
	s_waitcnt lgkmcnt(5)
	v_mfma_f32_32x32x16_bf16 v[18:33], v[240:243], v[222:225], v[18:33]
	v_mfma_f32_32x32x16_bf16 v[2:17], v[244:247], v[222:225], v[2:17]
	ds_read_b128 v[222:225], v234 offset:12288
	v_add_u32_e32 v233, s59, v176
	v_add_u32_e32 v230, v233, v175
	v_add_u32_e32 v234, v233, v174
	s_waitcnt lgkmcnt(3)
	v_mfma_f32_32x32x16_bf16 v[114:129], v[202:205], v[210:213], v[114:129]
	ds_read_b128 v[240:243], v230 offset:32768
	v_mfma_f32_32x32x16_bf16 v[98:113], v[206:209], v[210:213], v[98:113]
	ds_read_b128 v[244:247], v230 offset:36864
	s_waitcnt lgkmcnt(4)
	v_mfma_f32_32x32x16_bf16 v[82:97], v[202:205], v[214:217], v[82:97]
	ds_read_b128 v[248:251], v234
	v_mfma_f32_32x32x16_bf16 v[66:81], v[206:209], v[214:217], v[66:81]
	ds_read_b128 v[214:217], v234 offset:4096
	s_waitcnt lgkmcnt(5)
	v_mfma_f32_32x32x16_bf16 v[50:65], v[202:205], v[218:221], v[50:65]
	v_mfma_f32_32x32x16_bf16 v[34:49], v[206:209], v[218:221], v[34:49]
	ds_read_b128 v[218:221], v234 offset:8192
	s_waitcnt lgkmcnt(5)
	v_mfma_f32_32x32x16_bf16 v[18:33], v[202:205], v[222:225], v[18:33]
	v_mfma_f32_32x32x16_bf16 v[2:17], v[206:209], v[222:225], v[2:17]
	ds_read_b128 v[222:225], v234 offset:12288
	s_waitcnt vmcnt(0)
	s_waitcnt vmcnt(0) lgkmcnt(0)
	s_barrier
	s_cbranch_scc1 .Lgemm_exit_1274
	s_and_b32 s59, s56, 0x10000
	s_xor_b32 s60, s59, 0x10000
	s_add_i32 s57, s58, 1
	s_add_i32 s60, s60, 0
	s_cmp_lt_u32 s58, 21
	s_cselect_b64 vcc, -1, 0
	v_add_u32_e32 v233, s59, v201
	v_add_u32_e32 v230, v233, v175
	v_add_u32_e32 v234, v233, v174
	s_add_i32 s66, s60, 0x8000
	v_lshl_add_u64 v[226:227], v[160:161], 0, s[2:3]
	v_lshl_add_u64 v[228:229], v[144:145], 0, s[2:3]
	v_cndmask_b32_e32 v227, v229, v227, vcc
	v_cndmask_b32_e32 v226, v228, v226, vcc
	v_lshl_add_u64 v[226:227], v[0:1], 1, v[226:227]
	s_add_i32 m0, s60, s62
	v_lshl_add_u64 v[228:229], v[142:143], 0, s[2:3]
	global_load_lds_dwordx4 v[226:227], off
	v_lshl_add_u64 v[226:227], v[158:159], 0, s[2:3]
	v_cndmask_b32_e32 v227, v229, v227, vcc
	v_cndmask_b32_e32 v226, v228, v226, vcc
	v_lshl_add_u64 v[226:227], v[130:131], 1, v[226:227]
	s_add_i32 m0, s60, s63
	v_lshl_add_u64 v[228:229], v[140:141], 0, s[2:3]
	global_load_lds_dwordx4 v[226:227], off
	v_lshl_add_u64 v[226:227], v[156:157], 0, s[2:3]
	v_cndmask_b32_e32 v227, v229, v227, vcc
	v_cndmask_b32_e32 v226, v228, v226, vcc
	v_lshl_add_u64 v[226:227], v[132:133], 1, v[226:227]
	s_add_i32 m0, s60, s64
	v_lshl_add_u64 v[228:229], v[138:139], 0, s[2:3]
	global_load_lds_dwordx4 v[226:227], off
	v_lshl_add_u64 v[226:227], v[154:155], 0, s[2:3]
	v_cndmask_b32_e32 v226, v228, v226, vcc
	v_cndmask_b32_e32 v227, v229, v227, vcc
	s_add_i32 m0, s60, s65
	v_lshl_add_u64 v[226:227], v[134:135], 1, v[226:227]
	global_load_lds_dwordx4 v[226:227], off
	s_add_i32 m0, s66, s62
	v_lshl_add_u64 v[226:227], v[146:147], 0, s[2:3]
	global_load_lds_dwordx4 v[226:227], off
	s_add_i32 m0, s66, s63
	v_lshl_add_u64 v[226:227], v[148:149], 0, s[2:3]
	global_load_lds_dwordx4 v[226:227], off
	s_add_i32 m0, s66, s64
	v_lshl_add_u64 v[226:227], v[150:151], 0, s[2:3]
	global_load_lds_dwordx4 v[226:227], off
	v_lshl_add_u64 v[226:227], v[152:153], 0, s[2:3]
	s_add_i32 m0, s66, s65
	s_add_i32 s58, s59, 0
	global_load_lds_dwordx4 v[226:227], off
	ds_read_b128 v[202:205], v230 offset:32768
	ds_read_b128 v[206:209], v230 offset:36864
	ds_read_b128 v[210:213], v234
	v_mfma_f32_32x32x16_bf16 v[114:129], v[240:243], v[248:251], v[114:129]
	v_mfma_f32_32x32x16_bf16 v[98:113], v[244:247], v[248:251], v[98:113]
	v_mfma_f32_32x32x16_bf16 v[82:97], v[240:243], v[214:217], v[82:97]
	v_mfma_f32_32x32x16_bf16 v[66:81], v[244:247], v[214:217], v[66:81]
	ds_read_b128 v[214:217], v234 offset:4096
	v_mfma_f32_32x32x16_bf16 v[50:65], v[240:243], v[218:221], v[50:65]
	v_mfma_f32_32x32x16_bf16 v[34:49], v[244:247], v[218:221], v[34:49]
	ds_read_b128 v[218:221], v234 offset:8192
	v_mfma_f32_32x32x16_bf16 v[18:33], v[240:243], v[222:225], v[18:33]
	v_mfma_f32_32x32x16_bf16 v[2:17], v[244:247], v[222:225], v[2:17]
	ds_read_b128 v[222:225], v234 offset:12288
	s_branch .Lgemm_rot_1274

; #define MFMA(a, b, c) __builtin_amdgcn_mfma_f32_32x32x16_bf16((a), (b), (c), 0, 0, 0)
;     ...
;     auto issue_at = [&](int mm0, int nn0, int kt, int buf) {
;       char* lb = L0 + buf * BUFB;
; #pragma unroll
;       for (int i = 0; i < 4; ++i) {
;         const int seg = wv * 4 + i, row = seg * 8 + gl_row;
;         const int c = (lane & 7) ^ ((row >> 1) & 7);
;         const u16* ap = (kt < g.split) ? g.a0 + (size_t)(mm0 + row) * g.ld0 + kt * g.ks0 : g.a1 + (size_t)(mm0 + row) * g.ld1 + (kt - g.split) * 64;
;         __builtin_amdgcn_global_load_lds((const unsigned*)(ap + c * 8), (__attribute__((address_space(3))) unsigned*)(lb + seg * 1024 + lane * 16), 16, 0, 0);
;       }
; #pragma unroll
;       for (int i = 0; i < BN / 64; ++i) {
;         const int seg = wv * (BN / 64) + i, row = seg * 8 + gl_row;
;         const int c = (lane & 7) ^ ((row >> 1) & 7);
;         __builtin_amdgcn_global_load_lds((const unsigned*)(g.W + (size_t)(nn0 + row) * g.K + kt * 64 + c * 8),
;                                          (__attribute__((address_space(3))) unsigned*)(lb + 256 * 128 + seg * 1024 + lane * 16), 16, 0, 0);
;       }
;     ...
;     auto compute2 = [&](int buf) {
;       const char* lb = L0 + buf * BUFB;
; #pragma unroll
;       for (int ks = 0; ks < 4; ++ks) {
;         const int c = ks * 2 + hh;
;         bf16x8 wf[2], xf[MI];
; #pragma unroll
;         for (int j = 0; j < 2; ++j) { const int r = wn * 64 + j * 32 + l32; wf[j] = *(const bf16x8*)(lb + 256 * 128 + r * 128 + ((c ^ ((r >> 1) & 7)) << 4)); }
; #pragma unroll
;         for (int i = 0; i < MI; ++i) { const int r = wm * (MI * 32) + i * 32 + l32; xf[i] = *(const bf16x8*)(lb + r * 128 + ((c ^ ((r >> 1) & 7)) << 4)); }
; #pragma unroll
;         for (int i = 0; i < MI; ++i) {
;           acc[i][0] = MFMA(wf[0], xf[i], acc[i][0]);
;           acc[i][1] = MFMA(wf[1], xf[i], acc[i][1]);
;         }
;       }
.Lgemm_g1_1371:
	v_add_u32_e32 v0, s17, v172
	v_add_u32_e32 v175, v0, v170
	v_add_u32_e32 v0, v0, v169
	s_waitcnt lgkmcnt(3)
	v_mfma_f32_32x32x16_bf16 v[114:129], v[224:227], v[232:235], v[114:129]
	ds_read_b128 v[200:203], v175 offset:32768
	v_mfma_f32_32x32x16_bf16 v[98:113], v[228:231], v[232:235], v[98:113]
	ds_read_b128 v[204:207], v175 offset:36864
	s_waitcnt lgkmcnt(4)
	v_mfma_f32_32x32x16_bf16 v[82:97], v[224:227], v[240:243], v[82:97]
	ds_read_b128 v[208:211], v0
	v_mfma_f32_32x32x16_bf16 v[66:81], v[228:231], v[240:243], v[66:81]
	ds_read_b128 v[212:215], v0 offset:4096
	s_waitcnt lgkmcnt(5)
	v_mfma_f32_32x32x16_bf16 v[50:65], v[224:227], v[244:247], v[50:65]
	ds_read_b128 v[216:219], v0 offset:8192
	v_mfma_f32_32x32x16_bf16 v[34:49], v[228:231], v[244:247], v[34:49]
	ds_read_b128 v[220:223], v0 offset:12288
	s_waitcnt lgkmcnt(6)
	v_mfma_f32_32x32x16_bf16 v[18:33], v[224:227], v[248:251], v[18:33]
	v_mfma_f32_32x32x16_bf16 v[2:17], v[228:231], v[248:251], v[2:17]
	v_add_u32_e32 v0, s17, v171
	v_add_u32_e32 v175, v0, v170
	v_add_u32_e32 v0, v0, v169
	s_waitcnt lgkmcnt(3)
	v_mfma_f32_32x32x16_bf16 v[114:129], v[200:203], v[208:211], v[114:129]
	ds_read_b128 v[224:227], v175 offset:32768
	v_mfma_f32_32x32x16_bf16 v[98:113], v[204:207], v[208:211], v[98:113]
	ds_read_b128 v[228:231], v175 offset:36864
	s_waitcnt lgkmcnt(4)
	v_mfma_f32_32x32x16_bf16 v[82:97], v[200:203], v[212:215], v[82:97]
	ds_read_b128 v[232:235], v0
	v_mfma_f32_32x32x16_bf16 v[66:81], v[204:207], v[212:215], v[66:81]
	ds_read_b128 v[240:243], v0 offset:4096
	s_waitcnt lgkmcnt(5)
	v_mfma_f32_32x32x16_bf16 v[50:65], v[200:203], v[216:219], v[50:65]
	ds_read_b128 v[244:247], v0 offset:8192
	v_mfma_f32_32x32x16_bf16 v[34:49], v[204:207], v[216:219], v[34:49]
	ds_read_b128 v[248:251], v0 offset:12288
	s_waitcnt lgkmcnt(6)
	v_mfma_f32_32x32x16_bf16 v[18:33], v[200:203], v[220:223], v[18:33]
	v_mfma_f32_32x32x16_bf16 v[2:17], v[204:207], v[220:223], v[2:17]
	s_waitcnt vmcnt(0)
	s_waitcnt vmcnt(0) lgkmcnt(0)
	s_barrier
	s_cbranch_scc1 .Lgemm_exit_1371
	s_and_b32 s17, s16, 0x10000
	s_xor_b32 s43, s17, 0x10000
	s_add_i32 s43, s43, 0
	s_add_i32 s17, s17, 0
	v_add_u32_e32 v0, s17, v174
	v_add_u32_e32 v175, v0, v170
	v_add_u32_e32 v0, v0, v169
	s_add_i32 s64, s43, 0x8000
	s_add_i32 m0, s43, s60
	v_lshl_add_u64 v[176:177], v[152:153], 0, s[10:11]
	global_load_lds_dwordx4 v[176:177], off
	s_add_i32 m0, s43, s61
	v_lshl_add_u64 v[176:177], v[150:151], 0, s[10:11]
	global_load_lds_dwordx4 v[176:177], off
	s_add_i32 m0, s43, s62
	v_lshl_add_u64 v[176:177], v[148:149], 0, s[10:11]
	global_load_lds_dwordx4 v[176:177], off
	s_add_i32 m0, s43, s63
	v_lshl_add_u64 v[176:177], v[146:147], 0, s[10:11]
	global_load_lds_dwordx4 v[176:177], off
	s_add_i32 m0, s64, s60
	v_lshl_add_u64 v[176:177], v[144:145], 0, s[10:11]
	global_load_lds_dwordx4 v[176:177], off
	s_add_i32 m0, s64, s61
	v_lshl_add_u64 v[176:177], v[142:143], 0, s[10:11]
	global_load_lds_dwordx4 v[176:177], off
	s_add_i32 m0, s64, s62
	v_lshl_add_u64 v[176:177], v[140:141], 0, s[10:11]
	global_load_lds_dwordx4 v[176:177], off
	s_add_i32 m0, s64, s63
	v_lshl_add_u64 v[176:177], v[138:139], 0, s[10:11]
	global_load_lds_dwordx4 v[176:177], off
	ds_read_b128 v[200:203], v175 offset:32768
	ds_read_b128 v[204:207], v175 offset:36864
	ds_read_b128 v[208:211], v0
	ds_read_b128 v[212:215], v0 offset:4096
	ds_read_b128 v[216:219], v0 offset:8192
	ds_read_b128 v[220:223], v0 offset:12288
	v_mfma_f32_32x32x16_bf16 v[114:129], v[224:227], v[232:235], v[114:129]
	v_mfma_f32_32x32x16_bf16 v[98:113], v[228:231], v[232:235], v[98:113]
	v_mfma_f32_32x32x16_bf16 v[82:97], v[224:227], v[240:243], v[82:97]
	v_mfma_f32_32x32x16_bf16 v[66:81], v[228:231], v[240:243], v[66:81]
	v_mfma_f32_32x32x16_bf16 v[50:65], v[224:227], v[244:247], v[50:65]
	v_mfma_f32_32x32x16_bf16 v[34:49], v[228:231], v[244:247], v[34:49]
	v_mfma_f32_32x32x16_bf16 v[18:33], v[224:227], v[248:251], v[18:33]
	v_mfma_f32_32x32x16_bf16 v[2:17], v[228:231], v[248:251], v[2:17]
	s_branch .Lgemm_rot_1371
